# fox work queue order: four heads at a time (heads 0-3 longest-first, then heads 4-7) so the K/V rows in flight fit the XCD's L2
# speedup vs baseline: 1.0026x; 1.0026x over previous
.LBB0_655:
	s_or_b64 exec, exec, s[2:3]
	v_mov_b32_e32 v2, s18
	s_waitcnt lgkmcnt(0)
	s_barrier
	ds_read_b32 v2, v2
	s_movk_i32 s2, 0x7f
	s_waitcnt lgkmcnt(0)
	v_cmp_lt_i32_e32 vcc, s2, v2
	v_readfirstlane_b32 s11, v2
	s_mov_b64 s[2:3], -1
	s_cbranch_vccnz .LBB0_652
	s_bfe_u32 s2, s11, 0x40002
	s_lshl_b32 s2, s2, 3
	s_lshr_b32 s3, s11, 6
	s_lshl_b32 s3, s3, 2
	s_and_b32 s11, s11, 3
	s_or_b32 s11, s11, s2
	s_or_b32 s11, s11, s3
	s_and_b32 s10, s11, 7
	s_lshl_b32 s2, s11, 5
	s_and_b32 s58, s2, 0xffffff00
	s_sub_i32 s11, 0x1000, s58
	v_readlane_b32 s2, v253, 63
	s_sub_i32 s23, 0xf00, s58
	v_readlane_b32 s3, v252, 0
	v_add_u32_e32 v148, s23, v189
	s_lshl_b32 s14, s10, 7
	v_mov_b64_e32 v[146:147], s[2:3]
	s_movk_i32 s2, 0x1800
	v_mad_i64_i32 v[146:147], s[2:3], v148, s2, v[146:147]
	v_lshl_add_u64 v[146:147], v[146:147], 0, s[14:15]
	v_lshl_add_u64 v[146:147], v[146:147], 0, v[174:175]
	global_load_dwordx4 v[114:117], v[146:147], off
	global_load_dwordx4 v[106:109], v[146:147], off offset:32
	global_load_dwordx4 v[102:105], v[146:147], off offset:64
	global_load_dwordx4 v[98:101], v[146:147], off offset:96
	v_cmp_gt_i32_e32 vcc, s11, v0
	s_and_saveexec_b64 s[2:3], vcc
	s_cbranch_execz .Ldk_p1_done
	s_lshl_b32 s14, s10, 2
	v_lshl_add_u64 v[2:3], v[186:187], 0, s[14:15]
	v_mov_b32_e32 v6, v0
	s_mov_b64 s[12:13], 0x4000
	global_load_dword v130, v[2:3], off
	v_add_u32_e32 v6, 0x200, v6
	v_cmp_gt_i32_e32 vcc, s11, v6
	v_lshl_add_u64 v[2:3], v[2:3], 0, s[12:13]
	s_nop 1
	s_and_b64 exec, exec, vcc
	s_cbranch_execz .Ldk_p1_done
	global_load_dword v131, v[2:3], off
	v_add_u32_e32 v6, 0x200, v6
	v_cmp_gt_i32_e32 vcc, s11, v6
	v_lshl_add_u64 v[2:3], v[2:3], 0, s[12:13]
	s_nop 1
	s_and_b64 exec, exec, vcc
	s_cbranch_execz .Ldk_p1_done
	global_load_dword v132, v[2:3], off
	v_add_u32_e32 v6, 0x200, v6
	v_cmp_gt_i32_e32 vcc, s11, v6
	v_lshl_add_u64 v[2:3], v[2:3], 0, s[12:13]
	s_nop 1
	s_and_b64 exec, exec, vcc
	s_cbranch_execz .Ldk_p1_done
	global_load_dword v133, v[2:3], off
	v_add_u32_e32 v6, 0x200, v6
	v_cmp_gt_i32_e32 vcc, s11, v6
	v_lshl_add_u64 v[2:3], v[2:3], 0, s[12:13]
	s_nop 1
	s_and_b64 exec, exec, vcc
	s_cbranch_execz .Ldk_p1_done
	global_load_dword v134, v[2:3], off
	v_add_u32_e32 v6, 0x200, v6
	v_cmp_gt_i32_e32 vcc, s11, v6
	v_lshl_add_u64 v[2:3], v[2:3], 0, s[12:13]
	s_nop 1
	s_and_b64 exec, exec, vcc
	s_cbranch_execz .Ldk_p1_done
	global_load_dword v135, v[2:3], off
	v_add_u32_e32 v6, 0x200, v6
	v_cmp_gt_i32_e32 vcc, s11, v6
	v_lshl_add_u64 v[2:3], v[2:3], 0, s[12:13]
	s_nop 1
	s_and_b64 exec, exec, vcc
	s_cbranch_execz .Ldk_p1_done
	global_load_dword v136, v[2:3], off
	v_add_u32_e32 v6, 0x200, v6
	v_cmp_gt_i32_e32 vcc, s11, v6
	v_lshl_add_u64 v[2:3], v[2:3], 0, s[12:13]
	s_nop 1
	s_and_b64 exec, exec, vcc
	s_cbranch_execz .Ldk_p1_done
	global_load_dword v137, v[2:3], off
